# attention: p-mref subtraction folded into QK MFMA accumulator init (-64 VALU per iteration), plus epilogue/pool/ssq load batching
# speedup vs baseline: 1.0118x; 1.0046x over previous
; #define AT_LOAD(X, t) do { const size_t adv_ = (size_t)(t) * 64; sk##X = *(const u32x4*)(gk + adv_ * 1024); sv##X = *(const u32x4*)(gv + adv_ * 1024); if (rth) sr##X = *(const u32x4*)(gr + adv_ * 32); } while (0)
; __device__ __forceinline__ void attn_unit(LAS char* lds, const bf16_t* Qp, const bf16_t* KVp, const bf16_t* KRp, int ntiles, bf16_t* Yp, bool dry) {
;     ...
;     for (int t = 0; t < ntiles; t += 2) {
;         const int sb0 = (t & 2);
;         const bool more = (t + 2 < ntiles);
;         f32x16 pa0 = {}, pa1 = {}, pb0 = {}, pb1 = {};
;         AT_QK(sb0, pa0, pa1);
;         AT_QK(sb0 + 1, pb0, pb1);
;         if (t == 0) AT_SMPV(sb0, true, pa0, pa1); else AT_SMPV(sb0, false, pa0, pa1);
;         __builtin_amdgcn_sched_barrier(0);
;         if (more) { AT_LOAD(A, t + 2); AT_LOAD(B, t + 3); }
.Latt_iter:
	v_xor_b32_e32 v82, 0x80000000, v189
	v_mov_b32_e32 v83, v82
	v_mov_b32_e32 v84, v82
	v_mov_b32_e32 v85, v82
	v_mov_b32_e32 v86, v82
	v_mov_b32_e32 v87, v82
	v_mov_b32_e32 v88, v82
	v_mov_b32_e32 v89, v82
	v_mov_b32_e32 v90, v82
	v_mov_b32_e32 v91, v82
	v_mov_b32_e32 v92, v82
	v_mov_b32_e32 v93, v82
	v_mov_b32_e32 v94, v82
	v_mov_b32_e32 v95, v82
	v_mov_b32_e32 v96, v82
	v_mov_b32_e32 v97, v82
.Latt_loop:
	s_and_b32 s42, s35, 2
	s_mul_i32 s2, s42, 0x3400
	v_add_u32_e32 v0, s2, v209
	v_lshl_add_u32 v185, s42, 13, v208
	v_add_u32_e32 v184, 0x2000, v185
	s_cmp_gt_u32 s35, 33
	s_cbranch_scc1 .Latt_noload
	v_lshl_add_u64 v[178:179], s[88:89], 0, v[194:195]
	v_add_co_u32_e32 v180, vcc, 0x2f440000, v178
	s_nop 1
	v_addc_co_u32_e32 v181, vcc, 0, v179, vcc
	global_load_dwordx4 v[130:133], v[180:181], off
	global_load_dwordx4 v[134:137], v[180:181], off offset:1024
	v_lshl_add_u64 v[180:181], s[88:89], 0, v[192:193]
	s_and_saveexec_b64 s[16:17], s[38:39]
	s_cbranch_execz .Latt_l1
	v_add_co_u32_e32 v248, vcc, 0x3cc02000, v180
	s_nop 1
	v_addc_co_u32_e32 v249, vcc, 0, v181, vcc
	global_load_dwordx4 v[138:141], v[248:249], off

.Latt_noload:
	ds_read_b128 v[66:69], v0 offset:0
	ds_read_b128 v[70:73], v0 offset:6656
	ds_read_b128 v[74:77], v0 offset:32
	ds_read_b128 v[78:81], v0 offset:6688
	ds_read_b128 v[212:215], v0 offset:64
	ds_read_b128 v[240:243], v0 offset:6720
	ds_read_b128 v[244:247], v0 offset:96
	s_waitcnt lgkmcnt(6)
	v_mfma_f32_32x32x16_bf16 v[114:129], v[66:69], v[154:157], v[82:97]
	ds_read_b128 v[248:251], v0 offset:6752
	s_waitcnt lgkmcnt(6)
	v_mfma_f32_32x32x16_bf16 v[98:113], v[70:73], v[154:157], v[82:97]
	ds_read_b128 v[66:69], v0 offset:128
	s_waitcnt lgkmcnt(6)
	v_mfma_f32_32x32x16_bf16 v[114:129], v[74:77], v[158:161], v[114:129]
	ds_read_b128 v[70:73], v0 offset:6784
	s_waitcnt lgkmcnt(6)
	v_mfma_f32_32x32x16_bf16 v[98:113], v[78:81], v[158:161], v[98:113]
	ds_read_b128 v[74:77], v0 offset:160
	s_waitcnt lgkmcnt(6)
	v_mfma_f32_32x32x16_bf16 v[114:129], v[212:215], v[162:165], v[114:129]
	ds_read_b128 v[78:81], v0 offset:6816
	s_waitcnt lgkmcnt(6)
	v_mfma_f32_32x32x16_bf16 v[98:113], v[240:243], v[162:165], v[98:113]
	ds_read_b128 v[212:215], v0 offset:13312
	s_waitcnt lgkmcnt(6)
	v_mfma_f32_32x32x16_bf16 v[114:129], v[244:247], v[166:169], v[114:129]
	ds_read_b128 v[240:243], v0 offset:19968
	s_waitcnt lgkmcnt(6)
	v_mfma_f32_32x32x16_bf16 v[98:113], v[248:251], v[166:169], v[98:113]
	ds_read_b128 v[244:247], v0 offset:13344
	s_waitcnt lgkmcnt(6)
	v_mfma_f32_32x32x16_bf16 v[114:129], v[66:69], v[170:173], v[114:129]
	ds_read_b128 v[248:251], v0 offset:20000
	s_waitcnt lgkmcnt(6)
	v_mfma_f32_32x32x16_bf16 v[98:113], v[70:73], v[170:173], v[98:113]
	ds_read_b128 v[66:69], v0 offset:13376
	s_waitcnt lgkmcnt(6)
	v_mfma_f32_32x32x16_bf16 v[114:129], v[74:77], v[174:177], v[114:129]
	ds_read_b128 v[70:73], v0 offset:20032
	s_waitcnt lgkmcnt(6)
	v_mfma_f32_32x32x16_bf16 v[98:113], v[78:81], v[174:177], v[98:113]
	ds_read_b128 v[74:77], v0 offset:13408
	s_waitcnt lgkmcnt(6)
	v_mfma_f32_32x32x16_bf16 v[2:17], v[212:215], v[154:157], v[82:97]
	ds_read_b128 v[78:81], v0 offset:20064
	s_waitcnt lgkmcnt(6)
	v_mfma_f32_32x32x16_bf16 v[18:33], v[240:243], v[154:157], v[82:97]
	ds_read_b128 v[212:215], v0 offset:13440
	s_waitcnt lgkmcnt(6)
	v_mfma_f32_32x32x16_bf16 v[2:17], v[244:247], v[158:161], v[2:17]
	ds_read_b128 v[240:243], v0 offset:20096
	v_max3_f32 v211, v114, v115, v116
	v_max3_f32 v211, v211, v117, v118
	s_waitcnt lgkmcnt(6)
	v_mfma_f32_32x32x16_bf16 v[18:33], v[248:251], v[158:161], v[18:33]
	ds_read_b128 v[244:247], v0 offset:13472
	v_max3_f32 v211, v211, v119, v120
	v_max3_f32 v178, v98, v99, v100
	s_waitcnt lgkmcnt(6)
	v_mfma_f32_32x32x16_bf16 v[2:17], v[66:69], v[162:165], v[2:17]
	ds_read_b128 v[248:251], v0 offset:20128
	v_max3_f32 v211, v211, v121, v122
	v_max3_f32 v178, v178, v101, v102
	s_waitcnt lgkmcnt(6)
	v_mfma_f32_32x32x16_bf16 v[18:33], v[70:73], v[162:165], v[18:33]
	ds_read_b64_tr_b16 v[216:217], v185 offset:53248
	ds_read_b64_tr_b16 v[218:219], v185 offset:53760
	v_max3_f32 v211, v211, v123, v124
	v_max3_f32 v178, v178, v103, v104
	s_waitcnt lgkmcnt(7)
	v_mfma_f32_32x32x16_bf16 v[2:17], v[74:77], v[166:169], v[2:17]
	ds_read_b64_tr_b16 v[220:221], v185 offset:57344
	ds_read_b64_tr_b16 v[222:223], v185 offset:57856
	v_max3_f32 v211, v211, v125, v126
	v_max3_f32 v178, v178, v105, v106
	s_waitcnt lgkmcnt(8)
	v_mfma_f32_32x32x16_bf16 v[18:33], v[78:81], v[166:169], v[18:33]
	ds_read_b64_tr_b16 v[224:225], v185 offset:54272
	ds_read_b64_tr_b16 v[226:227], v185 offset:54784
	v_max3_f32 v211, v211, v127, v128
	v_max3_f32 v178, v178, v107, v108
	s_waitcnt lgkmcnt(9)
	v_mfma_f32_32x32x16_bf16 v[2:17], v[212:215], v[170:173], v[2:17]
	ds_read_b64_tr_b16 v[228:229], v185 offset:58368
	ds_read_b64_tr_b16 v[230:231], v185 offset:58880
	v_max_f32_e32 v211, v211, v129
	v_max3_f32 v178, v178, v109, v110
	s_waitcnt lgkmcnt(10)
	v_mfma_f32_32x32x16_bf16 v[18:33], v[240:243], v[170:173], v[18:33]
	ds_read_b64_tr_b16 v[232:233], v185 offset:55296
	ds_read_b64_tr_b16 v[234:235], v185 offset:55808
	v_max3_f32 v178, v178, v111, v112
	v_max_f32_e32 v178, v178, v113
	s_waitcnt lgkmcnt(11)
	v_mfma_f32_32x32x16_bf16 v[2:17], v[244:247], v[174:177], v[2:17]
	ds_read_b64_tr_b16 v[236:237], v185 offset:59392
	ds_read_b64_tr_b16 v[238:239], v185 offset:59904
	v_max_f32_e32 v211, v211, v178
	s_waitcnt lgkmcnt(12)
	v_mfma_f32_32x32x16_bf16 v[18:33], v[248:251], v[174:177], v[18:33]
	v_mov_b32_e32 v179, v211
	s_nop 1
	v_permlane32_swap_b32_e32 v179, v211
	v_max_f32_e32 v211, v211, v179
	v_cmp_lt_f32_e32 vcc, s70, v211
	s_cbranch_vccnz .Latt_rsA
.Latt_smA:
	v_exp_f32_e32 v114, v114
	v_exp_f32_e32 v115, v115
	v_exp_f32_e32 v116, v116
	v_exp_f32_e32 v117, v117
	v_exp_f32_e32 v118, v118
	v_exp_f32_e32 v119, v119
	v_exp_f32_e32 v120, v120
	v_exp_f32_e32 v121, v121
	s_nop 0
	v_cvt_pk_bf16_f32 v66, v114, v115
	v_cvt_pk_bf16_f32 v67, v116, v117
	v_cvt_pk_bf16_f32 v68, v118, v119
	v_cvt_pk_bf16_f32 v69, v120, v121
	v_add_f32_e32 v178, v114, v115
	v_add_f32_e32 v179, v116, v117
	v_add_f32_e32 v180, v118, v119
	v_add_f32_e32 v181, v120, v121
	v_add_f32_e32 v178, v178, v179
	v_add_f32_e32 v180, v180, v181
	v_add_f32_e32 v178, v178, v180
	v_add_f32_e32 v210, v210, v178
	ds_read_b64_tr_b16 v[240:241], v185 offset:56320
	ds_read_b64_tr_b16 v[242:243], v185 offset:56832
	ds_read_b64_tr_b16 v[244:245], v185 offset:60416
	s_waitcnt lgkmcnt(11)
	ds_read_b64_tr_b16 v[246:247], v185 offset:60928
	ds_read_b64_tr_b16 v[114:115], v184 offset:53248
	ds_read_b64_tr_b16 v[116:117], v184 offset:53760
	ds_read_b64_tr_b16 v[118:119], v184 offset:57344
	s_waitcnt lgkmcnt(11)
	ds_read_b64_tr_b16 v[120:121], v184 offset:57856
	v_exp_f32_e32 v122, v122
	v_exp_f32_e32 v123, v123
	v_exp_f32_e32 v124, v124
	v_mfma_f32_32x32x16_bf16 v[34:49], v[66:69], v[216:219], v[34:49]
	v_exp_f32_e32 v125, v125
	v_exp_f32_e32 v126, v126
	v_exp_f32_e32 v127, v127
	v_exp_f32_e32 v128, v128
	v_exp_f32_e32 v129, v129
	s_nop 0
	v_cvt_pk_bf16_f32 v70, v122, v123
	v_cvt_pk_bf16_f32 v71, v124, v125
	v_mfma_f32_32x32x16_bf16 v[50:65], v[66:69], v[220:223], v[50:65]
	v_cvt_pk_bf16_f32 v72, v126, v127
	v_cvt_pk_bf16_f32 v73, v128, v129
	v_add_f32_e32 v178, v122, v123
	v_add_f32_e32 v179, v124, v125
	v_add_f32_e32 v180, v126, v127
	v_add_f32_e32 v181, v128, v129
	v_add_f32_e32 v178, v178, v179
	v_add_f32_e32 v180, v180, v181
	v_add_f32_e32 v178, v178, v180
	v_add_f32_e32 v210, v210, v178
	ds_read_b64_tr_b16 v[122:123], v184 offset:54272
	ds_read_b64_tr_b16 v[124:125], v184 offset:54784
	ds_read_b64_tr_b16 v[126:127], v184 offset:58368
	s_waitcnt lgkmcnt(11)
	ds_read_b64_tr_b16 v[128:129], v184 offset:58880
	v_exp_f32_e32 v98, v98
	v_exp_f32_e32 v99, v99
	v_exp_f32_e32 v100, v100
	v_mfma_f32_32x32x16_bf16 v[34:49], v[70:73], v[224:227], v[34:49]
	v_exp_f32_e32 v101, v101
	v_exp_f32_e32 v102, v102
	v_exp_f32_e32 v103, v103
	v_exp_f32_e32 v104, v104
	v_exp_f32_e32 v105, v105
	s_nop 0
	v_cvt_pk_bf16_f32 v74, v98, v99
	v_cvt_pk_bf16_f32 v75, v100, v101
	v_mfma_f32_32x32x16_bf16 v[50:65], v[70:73], v[228:231], v[50:65]
	v_cvt_pk_bf16_f32 v76, v102, v103
	v_cvt_pk_bf16_f32 v77, v104, v105
	v_add_f32_e32 v178, v98, v99
	v_add_f32_e32 v179, v100, v101
	v_add_f32_e32 v180, v102, v103
	v_add_f32_e32 v181, v104, v105
	v_add_f32_e32 v178, v178, v179
	v_add_f32_e32 v180, v180, v181
	v_add_f32_e32 v178, v178, v180
	v_add_f32_e32 v210, v210, v178
	ds_read_b64_tr_b16 v[98:99], v184 offset:55296
	ds_read_b64_tr_b16 v[100:101], v184 offset:55808
	ds_read_b64_tr_b16 v[102:103], v184 offset:59392
	s_waitcnt lgkmcnt(11)
	ds_read_b64_tr_b16 v[104:105], v184 offset:59904
	v_exp_f32_e32 v106, v106
	v_exp_f32_e32 v107, v107
	v_exp_f32_e32 v108, v108
	v_mfma_f32_32x32x16_bf16 v[34:49], v[74:77], v[232:235], v[34:49]
	v_exp_f32_e32 v109, v109
	v_exp_f32_e32 v110, v110
	v_exp_f32_e32 v111, v111
	v_exp_f32_e32 v112, v112
	v_exp_f32_e32 v113, v113
	s_nop 0
	v_cvt_pk_bf16_f32 v78, v106, v107
	v_cvt_pk_bf16_f32 v79, v108, v109
	v_mfma_f32_32x32x16_bf16 v[50:65], v[74:77], v[236:239], v[50:65]
	v_cvt_pk_bf16_f32 v80, v110, v111
	v_cvt_pk_bf16_f32 v81, v112, v113
	v_add_f32_e32 v178, v106, v107
	v_add_f32_e32 v179, v108, v109
	v_add_f32_e32 v180, v110, v111
	v_add_f32_e32 v181, v112, v113
	v_add_f32_e32 v178, v178, v179
	v_add_f32_e32 v180, v180, v181
	v_add_f32_e32 v178, v178, v180
	v_add_f32_e32 v210, v210, v178
	ds_read_b64_tr_b16 v[106:107], v184 offset:56320
	ds_read_b64_tr_b16 v[108:109], v184 offset:56832
	ds_read_b64_tr_b16 v[110:111], v184 offset:60416
	s_waitcnt lgkmcnt(11)
	ds_read_b64_tr_b16 v[112:113], v184 offset:60928
	v_max3_f32 v211, v2, v3, v4
	v_max3_f32 v178, v18, v19, v20
	v_max3_f32 v211, v211, v5, v6
	v_mfma_f32_32x32x16_bf16 v[34:49], v[78:81], v[240:243], v[34:49]
	v_max3_f32 v178, v178, v21, v22
	v_max3_f32 v211, v211, v7, v8
	v_max3_f32 v178, v178, v23, v24
	v_max3_f32 v211, v211, v9, v10
	v_max3_f32 v178, v178, v25, v26
	v_max3_f32 v211, v211, v11, v12
	v_mfma_f32_32x32x16_bf16 v[50:65], v[78:81], v[244:247], v[50:65]
	v_max3_f32 v178, v178, v27, v28
	v_max3_f32 v211, v211, v13, v14
	v_max3_f32 v178, v178, v29, v30
	v_max3_f32 v211, v211, v15, v16
	v_max3_f32 v178, v178, v31, v32
	v_max_f32_e32 v211, v211, v17
	v_max_f32_e32 v178, v178, v33
	v_max_f32_e32 v211, v211, v178
	v_mov_b32_e32 v179, v211
	s_nop 1
	v_permlane32_swap_b32_e32 v179, v211
	v_max_f32_e32 v211, v211, v179
	v_cmp_lt_f32_e32 vcc, s70, v211
	s_cbranch_vccnz .Latt_rsB
; #define AT_STORE(X, slot) do { *(LAS u32x4*)(lds + A_K0 + (slot) * AK_BYTES + lk) = sk##X; *(LAS u32x4*)(lds + A_V0 + (slot) * AV_BYTES + lv) = sv##X; if (rth) *(LAS u32x4*)(lds + A_K0 + (slot) * AK_BYTES + lr) = sr##X; } while (0)
; __device__ __forceinline__ void attn_unit(LAS char* lds, const bf16_t* Qp, const bf16_t* KVp, const bf16_t* KRp, int ntiles, bf16_t* Yp, bool dry) {
;     ...
;         AT_SMPV(sb0 + 1, false, pb0, pb1);
;         if (more) { AT_STORE(A, sb0 ^ 2); AT_STORE(B, (sb0 ^ 2) + 1); }
.Latt_smB:
	v_exp_f32_e32 v2, v2
	v_exp_f32_e32 v3, v3
	v_exp_f32_e32 v4, v4
	v_exp_f32_e32 v5, v5
	v_exp_f32_e32 v6, v6
	v_exp_f32_e32 v7, v7
	v_exp_f32_e32 v8, v8
	v_exp_f32_e32 v9, v9
	s_nop 0
	v_cvt_pk_bf16_f32 v66, v2, v3
	v_cvt_pk_bf16_f32 v67, v4, v5
	v_cvt_pk_bf16_f32 v68, v6, v7
	v_cvt_pk_bf16_f32 v69, v8, v9
	v_add_f32_e32 v178, v2, v3
	v_add_f32_e32 v179, v4, v5
	v_add_f32_e32 v180, v6, v7
	v_add_f32_e32 v181, v8, v9
	v_add_f32_e32 v178, v178, v179
	v_add_f32_e32 v180, v180, v181
	v_add_f32_e32 v178, v178, v180
	v_add_f32_e32 v210, v210, v178
	v_exp_f32_e32 v10, v10
	v_exp_f32_e32 v11, v11
	v_exp_f32_e32 v12, v12
	v_mfma_f32_32x32x16_bf16 v[34:49], v[66:69], v[114:117], v[34:49]
	v_exp_f32_e32 v13, v13
	v_exp_f32_e32 v14, v14
	v_exp_f32_e32 v15, v15
	v_exp_f32_e32 v16, v16
	v_exp_f32_e32 v17, v17
	s_nop 0
	v_cvt_pk_bf16_f32 v70, v10, v11
	v_cvt_pk_bf16_f32 v71, v12, v13
	v_mfma_f32_32x32x16_bf16 v[50:65], v[66:69], v[118:121], v[50:65]
	v_cvt_pk_bf16_f32 v72, v14, v15
	v_cvt_pk_bf16_f32 v73, v16, v17
	v_add_f32_e32 v178, v10, v11
	v_add_f32_e32 v179, v12, v13
	v_add_f32_e32 v180, v14, v15
	v_add_f32_e32 v181, v16, v17
	v_add_f32_e32 v178, v178, v179
	v_add_f32_e32 v180, v180, v181
	v_add_f32_e32 v178, v178, v180
	v_add_f32_e32 v210, v210, v178
	v_exp_f32_e32 v18, v18
	v_exp_f32_e32 v19, v19
	v_exp_f32_e32 v20, v20
	s_waitcnt lgkmcnt(10)
	v_mfma_f32_32x32x16_bf16 v[34:49], v[70:73], v[122:125], v[34:49]
	v_exp_f32_e32 v21, v21
	v_exp_f32_e32 v22, v22
	v_exp_f32_e32 v23, v23
	v_exp_f32_e32 v24, v24
	v_exp_f32_e32 v25, v25
	s_nop 0
	v_cvt_pk_bf16_f32 v74, v18, v19
	v_cvt_pk_bf16_f32 v75, v20, v21
	s_waitcnt lgkmcnt(8)
	v_mfma_f32_32x32x16_bf16 v[50:65], v[70:73], v[126:129], v[50:65]
	v_cvt_pk_bf16_f32 v76, v22, v23
	v_cvt_pk_bf16_f32 v77, v24, v25
	v_add_f32_e32 v178, v18, v19
	v_add_f32_e32 v179, v20, v21
	v_add_f32_e32 v180, v22, v23
	v_add_f32_e32 v181, v24, v25
	v_add_f32_e32 v178, v178, v179
	v_add_f32_e32 v180, v180, v181
	v_add_f32_e32 v178, v178, v180
	v_add_f32_e32 v210, v210, v178
	v_exp_f32_e32 v26, v26
	v_exp_f32_e32 v27, v27
	v_exp_f32_e32 v28, v28
	s_waitcnt lgkmcnt(6)
	v_mfma_f32_32x32x16_bf16 v[34:49], v[74:77], v[98:101], v[34:49]
	v_exp_f32_e32 v29, v29
	v_exp_f32_e32 v30, v30
	v_exp_f32_e32 v31, v31
	v_exp_f32_e32 v32, v32
	v_exp_f32_e32 v33, v33
	s_nop 0
	v_cvt_pk_bf16_f32 v78, v26, v27
	v_cvt_pk_bf16_f32 v79, v28, v29
	s_waitcnt lgkmcnt(4)
	v_mfma_f32_32x32x16_bf16 v[50:65], v[74:77], v[102:105], v[50:65]
	v_cvt_pk_bf16_f32 v80, v30, v31
	v_cvt_pk_bf16_f32 v81, v32, v33
	v_add_f32_e32 v178, v26, v27
	v_add_f32_e32 v179, v28, v29
	v_add_f32_e32 v180, v30, v31
	v_add_f32_e32 v181, v32, v33
	v_add_f32_e32 v178, v178, v179
	v_add_f32_e32 v180, v180, v181
	v_add_f32_e32 v178, v178, v180
	v_add_f32_e32 v210, v210, v178
	s_waitcnt lgkmcnt(2)
	v_mfma_f32_32x32x16_bf16 v[34:49], v[78:81], v[106:109], v[34:49]
	s_waitcnt lgkmcnt(0)
	v_mfma_f32_32x32x16_bf16 v[50:65], v[78:81], v[110:113], v[50:65]
	s_cmp_gt_u32 s35, 33
	s_cbranch_scc1 .Latt_latch
	s_xor_b32 s14, s42, 2
	s_mul_i32 s17, s14, 0x3400
	s_add_i32 s16, s17, 0
	v_add_u32_e32 v2, s16, v190
	s_waitcnt vmcnt(3)
	ds_write_b128 v2, v[130:133]
	v_lshl_add_u32 v2, s14, 13, v201
	s_waitcnt vmcnt(2)
	ds_write_b128 v2, v[134:137] offset:53248
	s_and_saveexec_b64 s[14:15], s[0:1]
	s_xor_b64 s[14:15], exec, s[14:15]
	s_cbranch_execz .Latt_st1
	v_add_u32_e32 v3, s17, v200
	s_waitcnt vmcnt(1)
	ds_write_b128 v3, v[146:149] offset:13312
	s_waitcnt vmcnt(0)
	ds_write_b128 v2, v[150:153] offset:61440

.Latt_rsA:
	s_nop 15
	v_max_f32_e32 v211, 0, v211
	v_exp_f32_e64 v179, -v211
	s_nop 0
	s_and_saveexec_b64 s[2:3], s[40:41]
	ds_write_b32 v207, v179
	s_or_b64 exec, exec, s[2:3]
	s_waitcnt lgkmcnt(0)
	v_add_f32_e32 v189, v189, v211
	v_mul_f32_e32 v210, v210, v179
	ds_read_b128 v[66:69], v199 offset:0
	ds_read_b128 v[70:73], v199 offset:32
	ds_read_b128 v[74:77], v199 offset:64
	ds_read_b128 v[78:81], v199 offset:96
	v_sub_f32_e32 v82, v82, v211
	v_sub_f32_e32 v83, v83, v211
	v_sub_f32_e32 v84, v84, v211
	v_sub_f32_e32 v85, v85, v211
	v_sub_f32_e32 v86, v86, v211
	v_sub_f32_e32 v87, v87, v211
	v_sub_f32_e32 v88, v88, v211
	v_sub_f32_e32 v89, v89, v211
	v_sub_f32_e32 v90, v90, v211
	v_sub_f32_e32 v91, v91, v211
	v_sub_f32_e32 v92, v92, v211
	v_sub_f32_e32 v93, v93, v211
	v_sub_f32_e32 v94, v94, v211
	v_sub_f32_e32 v95, v95, v211
	v_sub_f32_e32 v96, v96, v211
	v_sub_f32_e32 v97, v97, v211
	v_sub_f32_e32 v114, v114, v211
	v_sub_f32_e32 v115, v115, v211
	v_sub_f32_e32 v116, v116, v211
	v_sub_f32_e32 v117, v117, v211
	v_sub_f32_e32 v118, v118, v211
	v_sub_f32_e32 v119, v119, v211
	v_sub_f32_e32 v120, v120, v211
	v_sub_f32_e32 v121, v121, v211
	v_sub_f32_e32 v122, v122, v211
	v_sub_f32_e32 v123, v123, v211
	v_sub_f32_e32 v124, v124, v211
	v_sub_f32_e32 v125, v125, v211
	v_sub_f32_e32 v126, v126, v211
	v_sub_f32_e32 v127, v127, v211
	v_sub_f32_e32 v128, v128, v211
	v_sub_f32_e32 v129, v129, v211
	v_sub_f32_e32 v98, v98, v211
	v_sub_f32_e32 v99, v99, v211
	v_sub_f32_e32 v100, v100, v211
	v_sub_f32_e32 v101, v101, v211
	v_sub_f32_e32 v102, v102, v211
	v_sub_f32_e32 v103, v103, v211
	v_sub_f32_e32 v104, v104, v211
	v_sub_f32_e32 v105, v105, v211
	v_sub_f32_e32 v106, v106, v211
	v_sub_f32_e32 v107, v107, v211
	v_sub_f32_e32 v108, v108, v211
	v_sub_f32_e32 v109, v109, v211
	v_sub_f32_e32 v110, v110, v211
	v_sub_f32_e32 v111, v111, v211
	v_sub_f32_e32 v112, v112, v211
	v_sub_f32_e32 v113, v113, v211
	v_sub_f32_e32 v2, v2, v211
	v_sub_f32_e32 v3, v3, v211
	v_sub_f32_e32 v4, v4, v211
	v_sub_f32_e32 v5, v5, v211
	v_sub_f32_e32 v6, v6, v211
	v_sub_f32_e32 v7, v7, v211
	v_sub_f32_e32 v8, v8, v211
	v_sub_f32_e32 v9, v9, v211
	v_sub_f32_e32 v10, v10, v211
	v_sub_f32_e32 v11, v11, v211
	v_sub_f32_e32 v12, v12, v211
	v_sub_f32_e32 v13, v13, v211
	v_sub_f32_e32 v14, v14, v211
	v_sub_f32_e32 v15, v15, v211
	v_sub_f32_e32 v16, v16, v211
	v_sub_f32_e32 v17, v17, v211
	v_sub_f32_e32 v18, v18, v211
	v_sub_f32_e32 v19, v19, v211
	v_sub_f32_e32 v20, v20, v211
	v_sub_f32_e32 v21, v21, v211
	v_sub_f32_e32 v22, v22, v211
	v_sub_f32_e32 v23, v23, v211
	v_sub_f32_e32 v24, v24, v211
	v_sub_f32_e32 v25, v25, v211
	v_sub_f32_e32 v26, v26, v211
	v_sub_f32_e32 v27, v27, v211
	v_sub_f32_e32 v28, v28, v211
	v_sub_f32_e32 v29, v29, v211
	v_sub_f32_e32 v30, v30, v211
	v_sub_f32_e32 v31, v31, v211
	v_sub_f32_e32 v32, v32, v211
	v_sub_f32_e32 v33, v33, v211
	s_waitcnt lgkmcnt(0)
	v_mul_f32_e32 v34, v34, v66
	v_mul_f32_e32 v50, v50, v66
	v_mul_f32_e32 v35, v35, v67
	v_mul_f32_e32 v51, v51, v67
	v_mul_f32_e32 v36, v36, v68
	v_mul_f32_e32 v52, v52, v68
	v_mul_f32_e32 v37, v37, v69
	v_mul_f32_e32 v53, v53, v69
	v_mul_f32_e32 v38, v38, v70
	v_mul_f32_e32 v54, v54, v70
	v_mul_f32_e32 v39, v39, v71
	v_mul_f32_e32 v55, v55, v71
	v_mul_f32_e32 v40, v40, v72
	v_mul_f32_e32 v56, v56, v72
	v_mul_f32_e32 v41, v41, v73
	v_mul_f32_e32 v57, v57, v73
	v_mul_f32_e32 v42, v42, v74
	v_mul_f32_e32 v58, v58, v74
	v_mul_f32_e32 v43, v43, v75
	v_mul_f32_e32 v59, v59, v75
	v_mul_f32_e32 v44, v44, v76
	v_mul_f32_e32 v60, v60, v76
	v_mul_f32_e32 v45, v45, v77
	v_mul_f32_e32 v61, v61, v77
	v_mul_f32_e32 v46, v46, v78
	v_mul_f32_e32 v62, v62, v78
	v_mul_f32_e32 v47, v47, v79
	v_mul_f32_e32 v63, v63, v79
	v_mul_f32_e32 v48, v48, v80
	v_mul_f32_e32 v64, v64, v80
	v_mul_f32_e32 v49, v49, v81
	v_mul_f32_e32 v65, v65, v81
	s_nop 1
	s_branch .Latt_smA
.Latt_rsB:
	s_nop 15
	v_max_f32_e32 v211, 0, v211
	v_exp_f32_e64 v179, -v211
	s_nop 0
	s_and_saveexec_b64 s[2:3], s[40:41]
	ds_write_b32 v207, v179
	s_or_b64 exec, exec, s[2:3]
	s_waitcnt lgkmcnt(0)
	v_add_f32_e32 v189, v189, v211
	v_mul_f32_e32 v210, v210, v179
	ds_read_b128 v[66:69], v199 offset:0
	ds_read_b128 v[70:73], v199 offset:32
	ds_read_b128 v[74:77], v199 offset:64
	ds_read_b128 v[78:81], v199 offset:96
	v_sub_f32_e32 v82, v82, v211
	v_sub_f32_e32 v83, v83, v211
	v_sub_f32_e32 v84, v84, v211
	v_sub_f32_e32 v85, v85, v211
	v_sub_f32_e32 v86, v86, v211
	v_sub_f32_e32 v87, v87, v211
	v_sub_f32_e32 v88, v88, v211
	v_sub_f32_e32 v89, v89, v211
	v_sub_f32_e32 v90, v90, v211
	v_sub_f32_e32 v91, v91, v211
	v_sub_f32_e32 v92, v92, v211
	v_sub_f32_e32 v93, v93, v211
	v_sub_f32_e32 v94, v94, v211
	v_sub_f32_e32 v95, v95, v211
	v_sub_f32_e32 v96, v96, v211
	v_sub_f32_e32 v97, v97, v211
	v_sub_f32_e32 v2, v2, v211
	v_sub_f32_e32 v3, v3, v211
	v_sub_f32_e32 v4, v4, v211
	v_sub_f32_e32 v5, v5, v211
	v_sub_f32_e32 v6, v6, v211
	v_sub_f32_e32 v7, v7, v211
	v_sub_f32_e32 v8, v8, v211
	v_sub_f32_e32 v9, v9, v211
	v_sub_f32_e32 v10, v10, v211
	v_sub_f32_e32 v11, v11, v211
	v_sub_f32_e32 v12, v12, v211
	v_sub_f32_e32 v13, v13, v211
	v_sub_f32_e32 v14, v14, v211
	v_sub_f32_e32 v15, v15, v211
	v_sub_f32_e32 v16, v16, v211
	v_sub_f32_e32 v17, v17, v211
	v_sub_f32_e32 v18, v18, v211
	v_sub_f32_e32 v19, v19, v211
	v_sub_f32_e32 v20, v20, v211
	v_sub_f32_e32 v21, v21, v211
	v_sub_f32_e32 v22, v22, v211
	v_sub_f32_e32 v23, v23, v211
	v_sub_f32_e32 v24, v24, v211
	v_sub_f32_e32 v25, v25, v211
	v_sub_f32_e32 v26, v26, v211
	v_sub_f32_e32 v27, v27, v211
	v_sub_f32_e32 v28, v28, v211
	v_sub_f32_e32 v29, v29, v211
	v_sub_f32_e32 v30, v30, v211
	v_sub_f32_e32 v31, v31, v211
	v_sub_f32_e32 v32, v32, v211
	v_sub_f32_e32 v33, v33, v211
	s_waitcnt lgkmcnt(0)
	v_mul_f32_e32 v34, v34, v66
	v_mul_f32_e32 v50, v50, v66
	v_mul_f32_e32 v35, v35, v67
	v_mul_f32_e32 v51, v51, v67
	v_mul_f32_e32 v36, v36, v68
	v_mul_f32_e32 v52, v52, v68
	v_mul_f32_e32 v37, v37, v69
	v_mul_f32_e32 v53, v53, v69
	v_mul_f32_e32 v38, v38, v70
	v_mul_f32_e32 v54, v54, v70
	v_mul_f32_e32 v39, v39, v71
	v_mul_f32_e32 v55, v55, v71
	v_mul_f32_e32 v40, v40, v72
	v_mul_f32_e32 v56, v56, v72
	v_mul_f32_e32 v41, v41, v73
	v_mul_f32_e32 v57, v57, v73
	v_mul_f32_e32 v42, v42, v74
	v_mul_f32_e32 v58, v58, v74
	v_mul_f32_e32 v43, v43, v75
	v_mul_f32_e32 v59, v59, v75
	v_mul_f32_e32 v44, v44, v76
	v_mul_f32_e32 v60, v60, v76
	v_mul_f32_e32 v45, v45, v77
	v_mul_f32_e32 v61, v61, v77
	v_mul_f32_e32 v46, v46, v78
	v_mul_f32_e32 v62, v62, v78
	v_mul_f32_e32 v47, v47, v79
	v_mul_f32_e32 v63, v63, v79
	v_mul_f32_e32 v48, v48, v80
	v_mul_f32_e32 v64, v64, v80
	v_mul_f32_e32 v49, v49, v81
	v_mul_f32_e32 v65, v65, v81
	s_nop 1
	s_branch .Latt_smB
